# prologue de-serialisation: differential-mixer unit issues its first K/V tile loads beside the Q loads (one exposed round trip instead of two)
# speedup vs baseline: 1.0072x; 1.0072x over previous
; #define LAS __attribute__((address_space(3)))
; __device__ __forceinline__ float pair_sum(float v) { float a, b; lohi(v, a, b); return a + b; }
; #define ATT_LOAD(i) do { const int kt_ = first + (i) * step; kreg = *(const u32x4*)(ksrc + (size_t)kt_ * 64 * NIN); vreg = *(const u32x4*)(vsrc + (size_t)kt_ * 64 * NIN); \
;         if (VAR == 0 && tid < 64) freg = fsrc[(size_t)kt_ * 256] + PFX[kt_ >> 2]; } while (0)
; template <int VAR>
; __device__ __forceinline__ void attn_unit(LAS unsigned char* lds, const AttnArgs& A, int b, int h, int qb, const int tid) {
;     ...
;     bf16x8 qr[4];
; #pragma unroll
;     for (int d0 = 0; d0 < 4; ++d0) qr[d0] = *(const bf16x8*)(Qp + (size_t)t * NIN + d0 * 16 + hi * 8);
;     const bf16_t* ksrc = Kp + (size_t)lane * NIN + wid * 8;
;     const bf16_t* vsrc = Vp + (size_t)(16 * (wid & 3) + (lane >> 2)) * NIN + (wid >> 2) * 32 + (lane & 3) * 8;
;     const float* fsrc = A.LFC + (rowbase + (size_t)(tid & 63)) * 4 + h;
;     u32x4 kreg, vreg; float freg = 0.f;
;     ...
;     float m1 = -1e30f, l1 = 0.f, m2 = -1e30f, l2 = 0.f, R = 1.f;
;     bool wdone = false;
;     LAS unsigned* DONE = (LAS unsigned*)(lds + MISC_OFF + 64);
;     f32x16 o[2], o2[2];
; #pragma unroll
;     for (int r = 0; r < 16; ++r) { o[0][r] = 0.f; o[1][r] = 0.f; o2[0][r] = 0.f; o2[1][r] = 0.f; }
;     float Ft = 0.f;
;     if (VAR == 0) Ft = A.LFC[(rowbase + t) * 4 + h] + PFX[qb];
;     const float slope2 = (VAR == 2) ? __builtin_amdgcn_exp2f(-2.0f * (float)(h + 1)) * LOG2E : 0.f;
;     float qkb1 = 0.f, qkb2 = 0.f;
;     if (VAR == 0 || VAR == 2) {
;         float s1 = 0.f, s2 = 0.f;
; #pragma unroll
;         for (int d0 = 0; d0 < 4; ++d0)
; #pragma unroll
;             for (int j = 0; j < 4; ++j) {
;                 const unsigned w = __builtin_bit_cast(u32x4, qr[d0])[j];
;                 const float a0 = __uint_as_float(w << 16), a1 = __uint_as_float(w & 0xffff0000u);
;                 if (d0 < 2) s1 += a0 * a0 + a1 * a1; else s2 += a0 * a0 + a1 * a1;
;             }
;         const float* km = A.KM + (((VAR == 2 ? 32 : 0) + b) * 4 + h) * 2;
;         if (VAR == 0) qkb1 = sqrtf(pair_sum(s1 + s2)) * sqrtf(km[0] + km[1]) * 1.01f;
;         else { qkb1 = sqrtf(pair_sum(s1)) * sqrtf(km[0]) * 1.01f; qkb2 = sqrtf(pair_sum(s2)) * sqrtf(km[1]) * 1.01f; }
;     }
;     ATT_LOAD(0); ATT_STORE(0);
.LBB0_450:
	s_and_b64 vcc, exec, s[8:9]
	s_cbranch_vccz .LBB0_478
	v_readfirstlane_b32 s28, v124
	s_ashr_i32 s49, s28, 6
	s_lshl_b32 s12, s49, 5
	s_add_i32 s50, s12, s80
	s_lshl_b32 s68, s73, 11
	s_mul_i32 s8, s73, 0xc00000
	s_add_u32 s8, s45, s8
	s_addc_u32 s9, s74, 0
	s_lshl_b32 s48, s72, 6
	s_lshl_b32 s10, s72, 7
	s_add_u32 s10, s8, s10
	s_addc_u32 s11, s9, 0
	v_or_b32_e32 v126, s50, v174
	s_waitcnt lgkmcnt(5)
	v_mov_b64_e32 v[2:3], s[10:11]
	v_mad_i64_i32 v[2:3], s[8:9], v126, s35, v[2:3]
	v_lshlrev_b32_e32 v0, 4, v175
	v_lshl_add_u64 v[2:3], v[2:3], 0, v[0:1]
	global_load_dwordx4 v[98:101], v[2:3], off offset:3072
	global_load_dwordx4 v[102:105], v[2:3], off offset:3104
	global_load_dwordx4 v[106:109], v[2:3], off offset:3136
	global_load_dwordx4 v[110:113], v[2:3], off offset:3168
	v_mul_u32_u24_e32 v4, 0xc00, v176
	s_lshl_b32 s59, s72, 3
	s_lshl_b32 s69, s73, 5
	v_mov_b32_e32 v5, v1
	v_lshlrev_b32_e32 v4, 1, v4
	s_or_b32 s59, s69, s59
	v_lshl_add_u64 v[2:3], s[10:11], 0, v[4:5]
	v_mov_b32_e32 v5, s59
	s_waitcnt lgkmcnt(3)
	global_load_dwordx2 v[10:11], v5, s[66:67] offset:1024
	s_not_b32 s51, s72
	v_lshlrev_b32_e32 v8, 3, v124
	s_lshl_b32 s51, s51, 1
	s_waitcnt lgkmcnt(0)
	v_and_b32_e32 v24, 24, v8
	v_cvt_f32_i32_e32 v8, s51
	v_lshrrev_b32_e32 v6, 2, v176
	s_lshl_b32 s38, s49, 4
	v_and_or_b32 v6, s38, 48, v6
	v_mul_u32_u24_e32 v4, 0xc00, v6
	v_mov_b32_e32 v7, v1
	v_lshlrev_b32_e32 v6, 1, v4
	v_exp_f32_e32 v25, v8
	v_lshl_add_u64 v[4:5], s[10:11], 0, v[6:7]
	s_and_b32 s39, s28, 0x3fffffc0
	s_ashr_i32 s28, s28, 3
	s_lshl_b32 s8, s49, 3
	s_and_b32 s38, s28, 0xffffffe0
	s_ashr_i32 s9, s8, 31
	s_lshl_b32 s28, s39, 2
	s_ashr_i32 s39, s38, 31
	v_lshl_add_u64 v[4:5], s[38:39], 1, v[4:5]
	v_lshl_add_u64 v[128:129], s[8:9], 1, v[2:3]
	v_lshlrev_b32_e32 v2, 1, v24
	v_mov_b32_e32 v3, v1
	v_lshl_add_u64 v[2:3], v[4:5], 0, v[2:3]
	s_mov_b64 s[8:9], 0xc00
	v_lshl_add_u64 v[130:131], v[2:3], 0, s[8:9]
	s_lshl_b32 s13, s79, 2
	s_or_b32 s70, s13, 3
	s_add_i32 s69, s28, 0
	s_mul_i32 s28, s70, 0x60000
	v_lshl_add_u64 v[222:223], v[128:129], 0, s[28:29]
	v_lshl_add_u64 v[226:227], v[130:131], 0, s[28:29]
	global_load_dwordx4 v[222:225], v[222:223], off offset:3584
	global_load_dwordx4 v[226:229], v[226:227], off offset:1024
	v_mov_b32_e32 v34, v1
	v_mov_b32_e32 v35, v1
	v_mov_b32_e32 v48, v1
	v_mov_b32_e32 v49, v1
	v_mul_f32_e32 v138, 0xbfb8aa3b, v25
	v_or_b32_e32 v141, s12, v174
	s_lshl_b32 s12, s78, 2
	v_mov_b32_e32 v36, v1
	v_mov_b32_e32 v37, v1
	v_mov_b32_e32 v38, v1
	v_mov_b32_e32 v39, v1
	v_mov_b32_e32 v40, v1
	v_mov_b32_e32 v41, v1
	v_mov_b32_e32 v42, v1
	v_mov_b32_e32 v43, v1
	v_mov_b32_e32 v44, v1
	v_mov_b32_e32 v45, v1
	v_mov_b32_e32 v46, v1
	v_mov_b32_e32 v47, v1
	v_mov_b64_e32 v[64:65], v[48:49]
	v_ashrrev_i32_e32 v127, 31, v126
	s_ashr_i32 s81, s50, 6
	s_add_i32 s82, s13, 4
	s_mov_b32 s70, 0
	s_or_b32 s83, s13, 2
	v_lshl_add_u32 v139, v174, 2, s69
	v_cmp_eq_u32_e64 s[10:11], 0, v176
	s_sub_i32 s84, 29, s12
	s_mov_b64 s[12:13], 0
	v_mov_b32_e32 v143, 0
	v_mov_b32_e32 v217, 0xf149f2ca
	s_movk_i32 s85, 0x2000
	v_mov_b32_e32 v144, 0xf149f2ca
	v_mov_b32_e32 v142, 0
	v_mov_b64_e32 v[62:63], v[46:47]
	v_mov_b64_e32 v[60:61], v[44:45]
	s_waitcnt vmcnt(4)
	v_and_b32_e32 v26, 0xffff0000, v98
	v_and_b32_e32 v28, 0xffff0000, v99
	v_lshlrev_b32_e32 v22, 16, v98
	v_lshlrev_b32_e32 v27, 16, v99
	v_and_b32_e32 v9, 0xffff0000, v101
	v_and_b32_e32 v8, 0xffff0000, v100
	s_waitcnt vmcnt(3)
	v_and_b32_e32 v15, 0xffff0000, v103
	v_and_b32_e32 v14, 0xffff0000, v102
	v_mul_f32_e32 v26, v26, v26
	v_mul_f32_e32 v28, v28, v28
	v_lshlrev_b32_e32 v7, 16, v101
	v_lshlrev_b32_e32 v6, 16, v100
	v_lshlrev_b32_e32 v13, 16, v103
	v_lshlrev_b32_e32 v12, 16, v102
	v_pk_mul_f32 v[8:9], v[8:9], v[8:9]
	v_pk_mul_f32 v[14:15], v[14:15], v[14:15]
	v_fmac_f32_e32 v26, v22, v22
	v_fmac_f32_e32 v28, v27, v27
	v_pk_fma_f32 v[6:7], v[6:7], v[6:7], v[8:9]
	v_pk_fma_f32 v[8:9], v[12:13], v[12:13], v[14:15]
	v_add_f32_e32 v14, v26, v28
	v_add_f32_e32 v6, v6, v14
	v_and_b32_e32 v19, 0xffff0000, v105
	v_and_b32_e32 v18, 0xffff0000, v104
	v_add_f32_e32 v6, v7, v6
	v_lshlrev_b32_e32 v17, 16, v105
	v_lshlrev_b32_e32 v16, 16, v104
	v_pk_mul_f32 v[18:19], v[18:19], v[18:19]
	v_add_f32_e32 v6, v8, v6
	s_waitcnt vmcnt(2)
	v_and_b32_e32 v30, 0xffff0000, v106
	v_and_b32_e32 v32, 0xffff0000, v107
	v_pk_fma_f32 v[12:13], v[16:17], v[16:17], v[18:19]
	v_add_f32_e32 v6, v9, v6
	v_lshlrev_b32_e32 v29, 16, v106
	v_lshlrev_b32_e32 v31, 16, v107
	v_and_b32_e32 v23, 0xffff0000, v109
	v_mul_f32_e32 v30, v30, v30
	v_mul_f32_e32 v32, v32, v32
	v_add_f32_e32 v6, v12, v6
	v_and_b32_e32 v22, 0xffff0000, v108
	v_lshlrev_b32_e32 v21, 16, v109
	v_lshlrev_b32_e32 v20, 16, v108
	v_fmac_f32_e32 v30, v29, v29
	v_fmac_f32_e32 v32, v31, v31
	v_add_f32_e32 v12, v13, v6
	v_pk_mul_f32 v[6:7], v[22:23], v[22:23]
	v_add_f32_e32 v15, v30, v32
	v_pk_fma_f32 v[6:7], v[20:21], v[20:21], v[6:7]
	s_waitcnt vmcnt(1)
; __device__ __forceinline__ float pair_sum(float v) { float a, b; lohi(v, a, b); return a + b; }
; #define ATT_LOAD(i) do { const int kt_ = first + (i) * step; kreg = *(const u32x4*)(ksrc + (size_t)kt_ * 64 * NIN); vreg = *(const u32x4*)(vsrc + (size_t)kt_ * 64 * NIN); \
;         if (VAR == 0 && tid < 64) freg = fsrc[(size_t)kt_ * 256] + PFX[kt_ >> 2]; } while (0)
; #define ATT_STORE(bf) do { *(LAS u32x4*)(lds + K_OFF + (bf) * 8192 + wid * 1024 + lane * 16) = kreg; *(LAS u32x4*)(lds + V_OFF + (bf) * 8192 + wid * 1024 + lane * 16) = vreg; \
;         if (VAR == 0 && tid < 64) FS[(bf) * 64 + tid] = freg; } while (0)
; template <int VAR>
; __device__ __forceinline__ void attn_unit(LAS unsigned char* lds, const AttnArgs& A, int b, int h, int qb, const int tid) {
;     ...
;             }
;         const float* km = A.KM + (((VAR == 2 ? 32 : 0) + b) * 4 + h) * 2;
;         if (VAR == 0) qkb1 = sqrtf(pair_sum(s1 + s2)) * sqrtf(km[0] + km[1]) * 1.01f;
;         else { qkb1 = sqrtf(pair_sum(s1)) * sqrtf(km[0]) * 1.01f; qkb2 = sqrtf(pair_sum(s2)) * sqrtf(km[1]) * 1.01f; }
;     }
;     ATT_LOAD(0); ATT_STORE(0);
;     if (n > 1) ATT_LOAD(1);
;     __syncthreads();
	v_and_b32_e32 v9, 0xffff0000, v111
	v_add_f32_e32 v6, v6, v15
	v_and_b32_e32 v8, 0xffff0000, v110
	v_add_f32_e32 v13, v7, v6
	v_lshlrev_b32_e32 v7, 16, v111
	v_lshlrev_b32_e32 v6, 16, v110
	v_pk_mul_f32 v[8:9], v[8:9], v[8:9]
	v_mov_b32_e32 v2, v12
	v_pk_fma_f32 v[6:7], v[6:7], v[6:7], v[8:9]
	s_nop 0
	v_permlane32_swap_b32_e32 v12, v2
	v_add_f32_e32 v6, v6, v13
	v_and_b32_e32 v9, 0xffff0000, v113
	v_and_b32_e32 v8, 0xffff0000, v112
	v_add_f32_e32 v2, v12, v2
	v_add_f32_e32 v13, v7, v6
	v_lshlrev_b32_e32 v7, 16, v113
	v_lshlrev_b32_e32 v6, 16, v112
	v_pk_mul_f32 v[8:9], v[8:9], v[8:9]
	v_mul_f32_e32 v3, 0x4f800000, v2
	v_cmp_gt_f32_e32 vcc, s96, v2
	v_pk_fma_f32 v[6:7], v[6:7], v[6:7], v[8:9]
	v_mov_b64_e32 v[58:59], v[42:43]
	v_cndmask_b32_e32 v12, v2, v3, vcc
	v_add_f32_e32 v6, v6, v13
	v_sqrt_f32_e32 v13, v12
	v_add_f32_e32 v14, v7, v6
	s_nop 0
	s_nop 0
	v_add_u32_e32 v15, -1, v13
	v_fma_f32 v16, -v15, v13, v12
	v_cmp_ge_f32_e64 s[8:9], 0, v16
	v_add_u32_e32 v16, 1, v13
	s_nop 0
	v_cndmask_b32_e64 v15, v13, v15, s[8:9]
	v_fma_f32 v13, -v16, v13, v12
	v_cmp_lt_f32_e64 s[8:9], 0, v13
	s_nop 0
	v_mov_b64_e32 v[56:57], v[40:41]
	v_cndmask_b32_e64 v13, v15, v16, s[8:9]
	s_waitcnt vmcnt(2)
	v_mul_f32_e32 v16, 0x4f800000, v10
	v_cmp_gt_f32_e64 s[8:9], s96, v10
	v_mul_f32_e32 v15, 0x37800000, v13
	v_cndmask_b32_e32 v13, v13, v15, vcc
	v_cndmask_b32_e64 v10, v10, v16, s[8:9]
	v_sqrt_f32_e32 v16, v10
	v_cmp_class_f32_e32 vcc, v12, v199
	v_mov_b64_e32 v[54:55], v[38:39]
	v_mov_b64_e32 v[52:53], v[36:37]
	v_cndmask_b32_e32 v13, v13, v12, vcc
	v_add_u32_e32 v12, -1, v16
	v_fma_f32 v15, -v12, v16, v10
	v_cmp_ge_f32_e32 vcc, 0, v15
	v_add_u32_e32 v15, 1, v16
	v_mov_b64_e32 v[50:51], v[34:35]
	v_cndmask_b32_e32 v12, v16, v12, vcc
	v_fma_f32 v16, -v15, v16, v10
	v_cmp_lt_f32_e32 vcc, 0, v16
	v_mov_b32_e32 v16, v14
	s_nop 1
	v_permlane32_swap_b32_e32 v14, v16
	v_add_f32_e32 v14, v14, v16
	v_cndmask_b32_e32 v12, v12, v15, vcc
	v_mul_f32_e32 v16, 0x4f800000, v14
	v_cmp_gt_f32_e32 vcc, s96, v14
	v_mul_f32_e32 v15, 0x37800000, v12
	v_cndmask_b32_e64 v12, v12, v15, s[8:9]
	v_cndmask_b32_e32 v14, v14, v16, vcc
	v_sqrt_f32_e32 v16, v14
	v_cmp_class_f32_e64 s[8:9], v10, v199
	s_nop 1
	v_cndmask_b32_e64 v15, v12, v10, s[8:9]
	v_add_u32_e32 v10, -1, v16
	v_fma_f32 v12, -v10, v16, v14
	v_cmp_ge_f32_e64 s[8:9], 0, v12
	v_add_u32_e32 v12, 1, v16
	v_fma_f32 v18, -v12, v16, v14
	v_cndmask_b32_e64 v10, v16, v10, s[8:9]
	s_mul_i32 s8, s79, 0x180000
	s_add_i32 s28, s8, 0xc0000
	v_lshl_add_u64 v[16:17], v[130:131], 0, s[28:29]
	global_load_dwordx4 v[114:117], v[16:17], off offset:1024
	v_lshl_add_u64 v[16:17], v[128:129], 0, s[28:29]
	global_load_dwordx4 v[118:121], v[16:17], off offset:3584
	v_cmp_lt_f32_e64 s[8:9], 0, v18
	v_mul_f32_e32 v16, 0x4f800000, v11
	s_nop 0
	v_cndmask_b32_e64 v10, v10, v12, s[8:9]
	v_cmp_gt_f32_e64 s[8:9], s96, v11
	v_mul_f32_e32 v12, 0x37800000, v10
	v_cndmask_b32_e32 v10, v10, v12, vcc
	v_cndmask_b32_e64 v11, v11, v16, s[8:9]
	v_sqrt_f32_e32 v16, v11
	v_cmp_class_f32_e32 vcc, v14, v199
	s_nop 1
	v_cndmask_b32_e32 v12, v10, v14, vcc
	v_add_u32_e32 v10, -1, v16
	v_fma_f32 v14, -v10, v16, v11
	v_cmp_ge_f32_e32 vcc, 0, v14
	v_add_u32_e32 v14, 1, v16
	s_nop 0
	v_cndmask_b32_e32 v10, v16, v10, vcc
	v_fma_f32 v16, -v14, v16, v11
	v_cmp_lt_f32_e32 vcc, 0, v16
	s_nop 1
	v_cndmask_b32_e32 v10, v10, v14, vcc
	v_mul_f32_e32 v14, 0x37800000, v10
	v_cndmask_b32_e64 v10, v10, v14, s[8:9]
	v_cmp_class_f32_e32 vcc, v11, v199
	s_mov_b32 s8, 0x3f8147ae
	s_nop 0
	v_cndmask_b32_e32 v14, v10, v11, vcc
	v_pk_mul_f32 v[10:11], v[14:15], v[12:13]
	s_nop 0
	v_pk_mul_f32 v[132:133], v[10:11], s[8:9] op_sel_hi:[1,0]
	s_lshl_b32 s8, s49, 10
	s_add_i32 s28, s8, 0
	v_lshl_add_u32 v125, v176, 4, s28
	s_waitcnt vmcnt(3)
	ds_write_b128 v125, v[222:225]
	s_waitcnt vmcnt(2)
	ds_write_b128 v125, v[226:229] offset:16384
	v_lshlrev_b32_e32 v2, 10, v175
	v_lshlrev_b32_e32 v3, 4, v174
	v_add3_u32 v136, 0, v2, v3
	v_lshlrev_b32_e32 v2, 1, v124
	v_lshlrev_b32_e32 v3, 2, v175
	v_lshrrev_b32_e32 v4, 2, v124
	v_and_b32_e32 v2, 32, v2
	v_and_or_b32 v4, v4, 3, v3
	v_add_u32_e32 v2, 0, v2
	v_lshlrev_b32_e32 v4, 6, v4
	s_mul_i32 s8, s49, 0xfffffc04
	v_add3_u32 v137, v2, v24, v4
	v_sub_u32_e32 v140, 0xffffff40, v3
	v_mov_b64_e32 v[2:3], v[34:35]
	v_mov_b64_e32 v[18:19], v[34:35]
	s_add_i32 s28, s28, s8
	v_cmp_gt_u32_e64 s[8:9], 32, v176
	v_mov_b64_e32 v[4:5], v[36:37]
	v_mov_b64_e32 v[6:7], v[38:39]
	v_mov_b64_e32 v[8:9], v[40:41]
	v_mov_b64_e32 v[10:11], v[42:43]
	v_mov_b64_e32 v[12:13], v[44:45]
	v_mov_b64_e32 v[14:15], v[46:47]
	v_mov_b64_e32 v[16:17], v[48:49]
	v_mov_b64_e32 v[20:21], v[36:37]
	v_mov_b64_e32 v[22:23], v[38:39]
	v_mov_b64_e32 v[24:25], v[40:41]
	v_mov_b64_e32 v[26:27], v[42:43]
	v_mov_b64_e32 v[28:29], v[44:45]
	v_mov_b64_e32 v[30:31], v[46:47]
	v_mov_b64_e32 v[32:33], v[48:49]
	s_waitcnt lgkmcnt(0)
	s_barrier
	s_cmp_eq_u32 s84, -3
	s_cbranch_scc0 .LBB0_453
